# v62 + P0 transposer loop without the per-block write-through store drains (the phase-0 grid barrier covers publication of blocks 0..7)
# baseline (speedup 1.0000x reference)
; #define LAS __attribute__((address_space(3)))
; #define LDS_WAIT() asm volatile("s_waitcnt lgkmcnt(0)" ::: "memory")
; __device__ __forceinline__ unsigned pk2(float lo, float hi) { return (unsigned)f2bf(lo) | ((unsigned)f2bf(hi) << 16); }
; __device__ __forceinline__ void p0_item_load(const P0Item& d, f32x4 (&v)[8], int lane) {
; #pragma unroll
;     for (int i = 0; i < 8; ++i) v[i] = __builtin_nontemporal_load((const f32x4*)(d.src + (size_t)(8 * i + (lane >> 3)) * d.N + 4 * (lane & 7)));
; }
; template <bool WT = false>
; __device__ __forceinline__ void p0_item_finish(const P0Item& d, const f32x4 (&v)[8], LAS float* scr, int lane) {
; #pragma unroll
;     for (int i = 0; i < 8; ++i) { LAS float* q = scr + (8 * i + (lane >> 3)) * 33 + 4 * (lane & 7); q[0] = v[i][0]; q[1] = v[i][1]; q[2] = v[i][2]; q[3] = v[i][3]; }
;     LDS_WAIT(); asm volatile("" ::: "memory");
;     const int c = lane & 7;
; #pragma unroll
;     for (int j = 0; j < 4; ++j) { const int n = (lane >> 3) + 8 * j; const LAS float* s = scr + (8 * c) * 33 + n;
;         v4u o; o.x = pk2(s[0 * 33], s[1 * 33]); o.y = pk2(s[2 * 33], s[3 * 33]); o.z = pk2(s[4 * 33], s[5 * 33]); o.w = pk2(s[6 * 33], s[7 * 33]);
;         if constexpr (WT) __builtin_amdgcn_raw_buffer_store_b128(o, __builtin_amdgcn_make_buffer_rsrc((void*)d.dst, 0, 0x7fffffff, 0x00020000), (int)(((size_t)n * d.ldt + 8 * c) * 2), 0, 16);
;         else *(v4u*)(d.dst + (size_t)n * d.ldt + 8 * c) = o; }
;     LDS_WAIT(); asm volatile("" ::: "memory");
; }
; __device__ __forceinline__ void tr_blocks(Frame& F, const Args& a, int T, int b_lo, int b_hi, bool tail) {
;     ...
;     da = p0_item_in(a, T, 8 * b_lo + w); p0_item_load(da, va, F.lane);
;     _Pragma("unroll 1") for (int b = b_lo; b < b_hi; b += 2) {
;         db = p0_item_in(a, T, 8 * (b + 1) + w); p0_item_load(db, vb, F.lane);
;         p0_item_finish<true>(da, va, scr, F.lane);
;         if (b > b_lo) { asm volatile("s_waitcnt vmcnt(12)" ::: "memory"); __syncthreads(); if (F.tid == 0) (void)xb_add(blk + 16 * (b - 1), 1u); }
;         da = p0_item_in(a, T, b + 2 < b_hi ? 8 * (b + 2) + w : (tail ? 448 : 8 * b + w)); p0_item_load(da, va, F.lane);
;         p0_item_finish<true>(db, vb, scr, F.lane);
;         asm volatile("s_waitcnt vmcnt(12)" ::: "memory"); __syncthreads(); if (F.tid == 0) (void)xb_add(blk + 16 * b, 1u);
.LBB0_114:
	s_lshl_b64 s[4:5], s[28:29], 12
	s_add_u32 s4, s35, s4
	s_addc_u32 s5, s53, s5
	s_ashr_i32 s39, s38, 31
	v_lshl_add_u64 v[34:35], s[38:39], 2, v[68:69]
	v_lshl_add_u64 v[58:59], v[34:35], 0, v[66:67]
	v_add_co_u32_e32 v38, vcc, s0, v58
	v_add_u32_e32 v75, 0x420, v74
	s_nop 0
	v_addc_co_u32_e32 v39, vcc, 0, v59, vcc
	v_add_co_u32_e32 v42, vcc, s1, v58
	global_load_dwordx4 v[34:37], v[58:59], off nt
	s_nop 0
	global_load_dwordx4 v[38:41], v[38:39], off offset:1024 nt
	v_addc_co_u32_e32 v43, vcc, 0, v59, vcc
	v_add_co_u32_e32 v46, vcc, s8, v58
	v_add_u32_e32 v76, 0x428, v74
	s_nop 0
	v_addc_co_u32_e32 v47, vcc, 0, v59, vcc
	v_add_co_u32_e32 v50, vcc, s9, v58
	global_load_dwordx4 v[42:45], v[42:43], off offset:2048 nt
	s_nop 0
	global_load_dwordx4 v[46:49], v[46:47], off offset:3072 nt
	v_addc_co_u32_e32 v51, vcc, 0, v59, vcc
	v_add_co_u32_e32 v54, vcc, s10, v58
	v_add_u32_e32 v77, 0x840, v74
	s_nop 0
	v_addc_co_u32_e32 v55, vcc, 0, v59, vcc
	v_add_co_u32_e32 v60, vcc, s11, v58
	global_load_dwordx4 v[50:53], v[50:51], off nt
	s_nop 0
	global_load_dwordx4 v[54:57], v[54:55], off offset:1024 nt
	v_addc_co_u32_e32 v61, vcc, 0, v59, vcc
	v_add_co_u32_e32 v62, vcc, s33, v58
	v_add_u32_e32 v78, 0x848, v74
	s_nop 0
	v_addc_co_u32_e32 v63, vcc, 0, v59, vcc
	global_load_dwordx4 v[58:61], v[60:61], off offset:2048 nt
	s_nop 0
	global_load_dwordx4 v[62:65], v[62:63], off offset:3072 nt
	v_add_u32_e32 v79, 0xc60, v74
	v_add_u32_e32 v80, 0xc68, v74
	v_add_u32_e32 v81, 0x1080, v74
	v_add_u32_e32 v82, 0x1088, v74
	v_add_u32_e32 v83, 0x14a0, v74
	v_add_u32_e32 v84, 0x14a8, v74
	v_add_u32_e32 v85, 0x18c0, v74
	v_add_u32_e32 v86, 0x18c8, v74
	v_add_u32_e32 v87, 0x1ce0, v74
	v_add_u32_e32 v88, 0x1ce8, v74
	s_waitcnt vmcnt(15)
	ds_write2_b32 v74, v2, v3 offset1:1
	ds_write2_b32 v74, v4, v5 offset0:2 offset1:3
	s_waitcnt vmcnt(14)
	ds_write2_b32 v75, v6, v7 offset1:1
	ds_write2_b32 v76, v8, v9 offset1:1
	s_waitcnt vmcnt(13)
	ds_write2_b32 v77, v10, v11 offset1:1
	ds_write2_b32 v78, v12, v13 offset1:1
	s_waitcnt vmcnt(12)
	ds_write2_b32 v79, v14, v15 offset1:1
	ds_write2_b32 v80, v16, v17 offset1:1
	s_waitcnt vmcnt(11)
	ds_write2_b32 v81, v18, v19 offset1:1
	ds_write2_b32 v82, v20, v21 offset1:1
	s_waitcnt vmcnt(10)
	ds_write2_b32 v83, v22, v23 offset1:1
	ds_write2_b32 v84, v24, v25 offset1:1
	s_waitcnt vmcnt(9)
	ds_write2_b32 v85, v26, v27 offset1:1
	ds_write2_b32 v86, v28, v29 offset1:1
	s_waitcnt vmcnt(8)
	ds_write2_b32 v87, v30, v31 offset1:1
	ds_write2_b32 v88, v32, v33 offset1:1
	s_waitcnt lgkmcnt(0)
	ds_read2_b32 v[6:7], v1 offset1:8
	ds_read2_b32 v[8:9], v1 offset0:33 offset1:41
	ds_read2_b32 v[10:11], v1 offset0:66 offset1:74
	ds_read2_b32 v[12:13], v1 offset0:99 offset1:107
	ds_read2_b32 v[14:15], v1 offset0:132 offset1:140
	s_waitcnt lgkmcnt(4)
	v_bfe_u32 v2, v6, 16, 1
	v_add3_u32 v2, v6, v2, s58
	s_waitcnt lgkmcnt(3)
	v_bfe_u32 v3, v8, 16, 1
	v_lshrrev_b32_e32 v2, 16, v2
	v_add3_u32 v3, v8, v3, s58
	ds_read2_b32 v[16:17], v1 offset0:165 offset1:173
	v_and_or_b32 v2, v3, s59, v2
	s_waitcnt lgkmcnt(3)
	v_bfe_u32 v3, v10, 16, 1
	v_add3_u32 v3, v10, v3, s58
	s_waitcnt lgkmcnt(2)
	v_bfe_u32 v4, v12, 16, 1
	ds_read2_b32 v[18:19], v1 offset0:198 offset1:206
	v_lshrrev_b32_e32 v3, 16, v3
	v_add3_u32 v4, v12, v4, s58
	ds_read2_b32 v[20:21], v1 offset0:231 offset1:239
	v_and_or_b32 v3, v4, s59, v3
	s_waitcnt lgkmcnt(3)
	v_bfe_u32 v4, v14, 16, 1
	v_add3_u32 v4, v14, v4, s58
	s_waitcnt lgkmcnt(2)
	v_bfe_u32 v5, v16, 16, 1
	v_lshrrev_b32_e32 v4, 16, v4
	v_add3_u32 v5, v16, v5, s58
	v_and_or_b32 v4, v5, s59, v4
	s_waitcnt lgkmcnt(1)
	v_bfe_u32 v5, v18, 16, 1
	v_add3_u32 v5, v18, v5, s58
	s_waitcnt lgkmcnt(0)
	v_bfe_u32 v6, v20, 16, 1
	v_lshrrev_b32_e32 v5, 16, v5
	v_add3_u32 v6, v20, v6, s58
	s_and_b32 s5, s5, 0xffff
	v_and_or_b32 v5, v6, s59, v5
	buffer_store_dwordx4 v[2:5], v70, s[4:7], 0 offen sc1
	v_bfe_u32 v8, v21, 16, 1
	v_add3_u32 v8, v21, v8, s58
	v_bfe_u32 v2, v7, 16, 1
	v_add3_u32 v2, v7, v2, s58
	v_bfe_u32 v3, v9, 16, 1
	v_lshrrev_b32_e32 v2, 16, v2
	v_add3_u32 v3, v9, v3, s58
	v_and_or_b32 v2, v3, s59, v2
	v_bfe_u32 v3, v11, 16, 1
	v_add3_u32 v3, v11, v3, s58
	v_bfe_u32 v4, v13, 16, 1
	v_lshrrev_b32_e32 v3, 16, v3
	v_add3_u32 v4, v13, v4, s58
	v_and_or_b32 v3, v4, s59, v3
	v_bfe_u32 v4, v15, 16, 1
	v_add3_u32 v4, v15, v4, s58
	v_bfe_u32 v5, v17, 16, 1
	v_lshrrev_b32_e32 v4, 16, v4
	v_add3_u32 v5, v17, v5, s58
	v_and_or_b32 v4, v5, s59, v4
	v_bfe_u32 v5, v19, 16, 1
	v_add3_u32 v5, v19, v5, s58
	v_lshrrev_b32_e32 v5, 16, v5
	ds_read2_b32 v[6:7], v1 offset0:16 offset1:24
	v_and_or_b32 v5, v8, s59, v5
	ds_read2_b32 v[8:9], v1 offset0:49 offset1:57
	ds_read2_b32 v[10:11], v1 offset0:82 offset1:90
	ds_read2_b32 v[12:13], v1 offset0:115 offset1:123
	buffer_store_dwordx4 v[2:5], v71, s[4:7], 0 offen sc1
	ds_read2_b32 v[14:15], v1 offset0:148 offset1:156
	ds_read2_b32 v[16:17], v1 offset0:181 offset1:189
	s_waitcnt lgkmcnt(5)
	v_bfe_u32 v2, v6, 16, 1
	v_add3_u32 v2, v6, v2, s58
	s_waitcnt lgkmcnt(4)
	v_bfe_u32 v3, v8, 16, 1
	v_lshrrev_b32_e32 v2, 16, v2
	v_add3_u32 v3, v8, v3, s58
	v_and_or_b32 v2, v3, s59, v2
	s_waitcnt lgkmcnt(3)
	v_bfe_u32 v3, v10, 16, 1
	v_add3_u32 v3, v10, v3, s58
	s_waitcnt lgkmcnt(2)
	v_bfe_u32 v4, v12, 16, 1
	ds_read2_b32 v[18:19], v1 offset0:214 offset1:222
	v_lshrrev_b32_e32 v3, 16, v3
	v_add3_u32 v4, v12, v4, s58
	ds_read2_b32 v[20:21], v1 offset0:247 offset1:255
	v_and_or_b32 v3, v4, s59, v3
	s_waitcnt lgkmcnt(3)
	v_bfe_u32 v4, v14, 16, 1
	v_add3_u32 v4, v14, v4, s58
	s_waitcnt lgkmcnt(2)
	v_bfe_u32 v5, v16, 16, 1
	v_lshrrev_b32_e32 v4, 16, v4
	v_add3_u32 v5, v16, v5, s58
	v_and_or_b32 v4, v5, s59, v4
	s_waitcnt lgkmcnt(1)
	v_bfe_u32 v5, v18, 16, 1
	v_add3_u32 v5, v18, v5, s58
	s_waitcnt lgkmcnt(0)
	v_bfe_u32 v6, v20, 16, 1
	v_lshrrev_b32_e32 v5, 16, v5
	v_add3_u32 v6, v20, v6, s58
	v_and_or_b32 v5, v6, s59, v5
	buffer_store_dwordx4 v[2:5], v72, s[4:7], 0 offen sc1
	v_bfe_u32 v6, v21, 16, 1
	v_add3_u32 v6, v21, v6, s58
	v_bfe_u32 v2, v7, 16, 1
	v_add3_u32 v2, v7, v2, s58
	v_bfe_u32 v3, v9, 16, 1
	v_lshrrev_b32_e32 v2, 16, v2
	v_add3_u32 v3, v9, v3, s58
	v_and_or_b32 v2, v3, s59, v2
	v_bfe_u32 v3, v11, 16, 1
	v_add3_u32 v3, v11, v3, s58
	v_bfe_u32 v4, v13, 16, 1
	v_lshrrev_b32_e32 v3, 16, v3
	v_add3_u32 v4, v13, v4, s58
	v_and_or_b32 v3, v4, s59, v3
	v_bfe_u32 v4, v15, 16, 1
	v_add3_u32 v4, v15, v4, s58
	v_bfe_u32 v5, v17, 16, 1
	v_lshrrev_b32_e32 v4, 16, v4
	v_add3_u32 v5, v17, v5, s58
	v_and_or_b32 v4, v5, s59, v4
	v_bfe_u32 v5, v19, 16, 1
	v_add3_u32 v5, v19, v5, s58
	v_lshrrev_b32_e32 v5, 16, v5
	v_and_or_b32 v5, v6, s59, v5
	buffer_store_dwordx4 v[2:5], v73, s[4:7], 0 offen sc1
	s_waitcnt lgkmcnt(0)
	s_cmp_eq_u32 s57, 16
	s_cbranch_scc1 .LBB0_119
; __device__ __forceinline__ unsigned xb_add(unsigned* p, unsigned v) { return __hip_atomic_fetch_add(p, v, __ATOMIC_RELAXED, __HIP_MEMORY_SCOPE_AGENT); }
; __device__ __forceinline__ void tr_blocks(Frame& F, const Args& a, int T, int b_lo, int b_hi, bool tail) {
;     ...
;         if (b > b_lo) { asm volatile("s_waitcnt vmcnt(12)" ::: "memory"); __syncthreads(); if (F.tid == 0) (void)xb_add(blk + 16 * (b - 1), 1u); }
;         da = p0_item_in(a, T, b + 2 < b_hi ? 8 * (b + 2) + w : (tail ? 448 : 8 * b + w)); p0_item_load(da, va, F.lane);
;         p0_item_finish<true>(db, vb, scr, F.lane);
;         asm volatile("s_waitcnt vmcnt(12)" ::: "memory"); __syncthreads(); if (F.tid == 0) (void)xb_add(blk + 16 * b, 1u);
	s_barrier
	s_and_saveexec_b64 s[4:5], s[2:3]
	s_cbranch_execz .LBB0_118
	s_mov_b64 s[38:39], exec
	v_mbcnt_lo_u32_b32 v2, s38, 0
	v_mbcnt_hi_u32_b32 v2, s39, v2
	v_cmp_eq_u32_e32 vcc, 0, v2
	s_and_b64 s[40:41], exec, vcc
	s_mov_b64 exec, s[40:41]
	s_cbranch_execz .LBB0_118
	s_bcnt1_i32_b64 s28, s[38:39]
	v_mov_b32_e32 v2, s28
	global_atomic_add v67, v2, s[30:31]

; #define LAS __attribute__((address_space(3)))
; #define LDS_WAIT() asm volatile("s_waitcnt lgkmcnt(0)" ::: "memory")
; __device__ __forceinline__ unsigned pk2(float lo, float hi) { return (unsigned)f2bf(lo) | ((unsigned)f2bf(hi) << 16); }
; __device__ __forceinline__ unsigned xb_add(unsigned* p, unsigned v) { return __hip_atomic_fetch_add(p, v, __ATOMIC_RELAXED, __HIP_MEMORY_SCOPE_AGENT); }
; __device__ __forceinline__ void p0_item_load(const P0Item& d, f32x4 (&v)[8], int lane) {
; #pragma unroll
;     for (int i = 0; i < 8; ++i) v[i] = __builtin_nontemporal_load((const f32x4*)(d.src + (size_t)(8 * i + (lane >> 3)) * d.N + 4 * (lane & 7)));
; }
; template <bool WT = false>
; __device__ __forceinline__ void p0_item_finish(const P0Item& d, const f32x4 (&v)[8], LAS float* scr, int lane) {
; #pragma unroll
;     for (int i = 0; i < 8; ++i) { LAS float* q = scr + (8 * i + (lane >> 3)) * 33 + 4 * (lane & 7); q[0] = v[i][0]; q[1] = v[i][1]; q[2] = v[i][2]; q[3] = v[i][3]; }
;     LDS_WAIT(); asm volatile("" ::: "memory");
;     const int c = lane & 7;
; #pragma unroll
;     for (int j = 0; j < 4; ++j) { const int n = (lane >> 3) + 8 * j; const LAS float* s = scr + (8 * c) * 33 + n;
;         v4u o; o.x = pk2(s[0 * 33], s[1 * 33]); o.y = pk2(s[2 * 33], s[3 * 33]); o.z = pk2(s[4 * 33], s[5 * 33]); o.w = pk2(s[6 * 33], s[7 * 33]);
;         if constexpr (WT) __builtin_amdgcn_raw_buffer_store_b128(o, __builtin_amdgcn_make_buffer_rsrc((void*)d.dst, 0, 0x7fffffff, 0x00020000), (int)(((size_t)n * d.ldt + 8 * c) * 2), 0, 16);
;         else *(v4u*)(d.dst + (size_t)n * d.ldt + 8 * c) = o; }
;     LDS_WAIT(); asm volatile("" ::: "memory");
; }
; __device__ __forceinline__ void tr_blocks(Frame& F, const Args& a, int T, int b_lo, int b_hi, bool tail) {
;     ...
;         da = p0_item_in(a, T, b + 2 < b_hi ? 8 * (b + 2) + w : (tail ? 448 : 8 * b + w)); p0_item_load(da, va, F.lane);
;         p0_item_finish<true>(db, vb, scr, F.lane);
;         asm volatile("s_waitcnt vmcnt(12)" ::: "memory"); __syncthreads(); if (F.tid == 0) (void)xb_add(blk + 16 * b, 1u);
.LBB0_124:
	s_ashr_i32 s5, s4, 31
	v_lshl_add_u64 v[2:3], s[4:5], 2, v[68:69]
	v_lshl_add_u64 v[26:27], v[2:3], 0, v[66:67]
	v_add_co_u32_e32 v6, vcc, 0x70000, v26
	s_and_b32 s5, s55, 0xffff
	s_nop 0
	v_addc_co_u32_e32 v7, vcc, 0, v27, vcc
	v_add_co_u32_e32 v10, vcc, 0xe0000, v26
	global_load_dwordx4 v[2:5], v[26:27], off nt
	s_nop 0
	global_load_dwordx4 v[6:9], v[6:7], off offset:1024 nt
	v_addc_co_u32_e32 v11, vcc, 0, v27, vcc
	v_add_co_u32_e32 v14, vcc, 0x150000, v26
	s_mov_b32 s4, s54
	s_nop 0
	v_addc_co_u32_e32 v15, vcc, 0, v27, vcc
	v_add_co_u32_e32 v18, vcc, 0x1c1000, v26
	global_load_dwordx4 v[10:13], v[10:11], off offset:2048 nt
	s_nop 0
	global_load_dwordx4 v[14:17], v[14:15], off offset:3072 nt
	v_addc_co_u32_e32 v19, vcc, 0, v27, vcc
	v_add_co_u32_e32 v22, vcc, 0x231000, v26
	s_nop 1
	v_addc_co_u32_e32 v23, vcc, 0, v27, vcc
	v_add_co_u32_e32 v28, vcc, 0x2a1000, v26
	global_load_dwordx4 v[18:21], v[18:19], off nt
	s_nop 0
	global_load_dwordx4 v[22:25], v[22:23], off offset:1024 nt
	v_addc_co_u32_e32 v29, vcc, 0, v27, vcc
	v_add_co_u32_e32 v30, vcc, 0x311000, v26
	s_nop 1
	v_addc_co_u32_e32 v31, vcc, 0, v27, vcc
	global_load_dwordx4 v[26:29], v[28:29], off offset:2048 nt
	s_nop 0
	global_load_dwordx4 v[30:33], v[30:31], off offset:3072 nt
	s_waitcnt vmcnt(19)
	ds_write2_b32 v74, v34, v35 offset1:1
	ds_write2_b32 v74, v36, v37 offset0:2 offset1:3
	s_waitcnt vmcnt(18)
	ds_write2_b32 v75, v38, v39 offset1:1
	ds_write2_b32 v76, v40, v41 offset1:1
	s_waitcnt vmcnt(17)
	ds_write2_b32 v77, v42, v43 offset1:1
	ds_write2_b32 v78, v44, v45 offset1:1
	s_waitcnt vmcnt(16)
	ds_write2_b32 v79, v46, v47 offset1:1
	ds_write2_b32 v80, v48, v49 offset1:1
	s_waitcnt vmcnt(15)
	ds_write2_b32 v81, v50, v51 offset1:1
	ds_write2_b32 v82, v52, v53 offset1:1
	s_waitcnt vmcnt(14)
	ds_write2_b32 v83, v54, v55 offset1:1
	ds_write2_b32 v84, v56, v57 offset1:1
	s_waitcnt vmcnt(13)
	ds_write2_b32 v85, v58, v59 offset1:1
	ds_write2_b32 v86, v60, v61 offset1:1
	s_waitcnt vmcnt(12)
	ds_write2_b32 v87, v62, v63 offset1:1
	ds_write2_b32 v88, v64, v65 offset1:1
	s_waitcnt lgkmcnt(0)
	ds_read2_b32 v[38:39], v1 offset1:8
	ds_read2_b32 v[40:41], v1 offset0:33 offset1:41
	ds_read2_b32 v[42:43], v1 offset0:66 offset1:74
	ds_read2_b32 v[44:45], v1 offset0:99 offset1:107
	ds_read2_b32 v[46:47], v1 offset0:132 offset1:140
	s_waitcnt lgkmcnt(4)
	v_bfe_u32 v34, v38, 16, 1
	v_add3_u32 v34, v38, v34, s58
	s_waitcnt lgkmcnt(3)
	v_bfe_u32 v35, v40, 16, 1
	v_lshrrev_b32_e32 v34, 16, v34
	v_add3_u32 v35, v40, v35, s58
	ds_read2_b32 v[48:49], v1 offset0:165 offset1:173
	v_and_or_b32 v34, v35, s59, v34
	s_waitcnt lgkmcnt(3)
	v_bfe_u32 v35, v42, 16, 1
	v_add3_u32 v35, v42, v35, s58
	s_waitcnt lgkmcnt(2)
	v_bfe_u32 v36, v44, 16, 1
	ds_read2_b32 v[50:51], v1 offset0:198 offset1:206
	v_lshrrev_b32_e32 v35, 16, v35
	v_add3_u32 v36, v44, v36, s58
	ds_read2_b32 v[52:53], v1 offset0:231 offset1:239
	v_and_or_b32 v35, v36, s59, v35
	s_waitcnt lgkmcnt(3)
	v_bfe_u32 v36, v46, 16, 1
	v_add3_u32 v36, v46, v36, s58
	s_waitcnt lgkmcnt(2)
	v_bfe_u32 v37, v48, 16, 1
	v_lshrrev_b32_e32 v36, 16, v36
	v_add3_u32 v37, v48, v37, s58
	v_and_or_b32 v36, v37, s59, v36
	s_waitcnt lgkmcnt(1)
	v_bfe_u32 v37, v50, 16, 1
	v_add3_u32 v37, v50, v37, s58
	s_waitcnt lgkmcnt(0)
	v_bfe_u32 v38, v52, 16, 1
	v_lshrrev_b32_e32 v37, 16, v37
	v_add3_u32 v38, v52, v38, s58
	v_and_or_b32 v37, v38, s59, v37
	buffer_store_dwordx4 v[34:37], v70, s[4:7], 0 offen sc1
	v_bfe_u32 v40, v53, 16, 1
	v_add3_u32 v40, v53, v40, s58
	v_bfe_u32 v34, v39, 16, 1
	v_add3_u32 v34, v39, v34, s58
	v_bfe_u32 v35, v41, 16, 1
	v_lshrrev_b32_e32 v34, 16, v34
	v_add3_u32 v35, v41, v35, s58
	v_and_or_b32 v34, v35, s59, v34
	v_bfe_u32 v35, v43, 16, 1
	v_add3_u32 v35, v43, v35, s58
	v_bfe_u32 v36, v45, 16, 1
	v_lshrrev_b32_e32 v35, 16, v35
	v_add3_u32 v36, v45, v36, s58
	v_and_or_b32 v35, v36, s59, v35
	v_bfe_u32 v36, v47, 16, 1
	v_add3_u32 v36, v47, v36, s58
	v_bfe_u32 v37, v49, 16, 1
	v_lshrrev_b32_e32 v36, 16, v36
	v_add3_u32 v37, v49, v37, s58
	v_and_or_b32 v36, v37, s59, v36
	v_bfe_u32 v37, v51, 16, 1
	v_add3_u32 v37, v51, v37, s58
	v_lshrrev_b32_e32 v37, 16, v37
	ds_read2_b32 v[38:39], v1 offset0:16 offset1:24
	v_and_or_b32 v37, v40, s59, v37
	ds_read2_b32 v[40:41], v1 offset0:49 offset1:57
	ds_read2_b32 v[42:43], v1 offset0:82 offset1:90
	ds_read2_b32 v[44:45], v1 offset0:115 offset1:123
	buffer_store_dwordx4 v[34:37], v71, s[4:7], 0 offen sc1
	ds_read2_b32 v[46:47], v1 offset0:148 offset1:156
	ds_read2_b32 v[48:49], v1 offset0:181 offset1:189
	s_waitcnt lgkmcnt(5)
	v_bfe_u32 v34, v38, 16, 1
	v_add3_u32 v34, v38, v34, s58
	s_waitcnt lgkmcnt(4)
	v_bfe_u32 v35, v40, 16, 1
	v_lshrrev_b32_e32 v34, 16, v34
	v_add3_u32 v35, v40, v35, s58
	v_and_or_b32 v34, v35, s59, v34
	s_waitcnt lgkmcnt(3)
	v_bfe_u32 v35, v42, 16, 1
	v_add3_u32 v35, v42, v35, s58
	s_waitcnt lgkmcnt(2)
	v_bfe_u32 v36, v44, 16, 1
	ds_read2_b32 v[50:51], v1 offset0:214 offset1:222
	v_lshrrev_b32_e32 v35, 16, v35
	v_add3_u32 v36, v44, v36, s58
	ds_read2_b32 v[52:53], v1 offset0:247 offset1:255
	v_and_or_b32 v35, v36, s59, v35
	s_waitcnt lgkmcnt(3)
	v_bfe_u32 v36, v46, 16, 1
	v_add3_u32 v36, v46, v36, s58
	s_waitcnt lgkmcnt(2)
	v_bfe_u32 v37, v48, 16, 1
	v_lshrrev_b32_e32 v36, 16, v36
	v_add3_u32 v37, v48, v37, s58
	v_and_or_b32 v36, v37, s59, v36
	s_waitcnt lgkmcnt(1)
	v_bfe_u32 v37, v50, 16, 1
	v_add3_u32 v37, v50, v37, s58
	s_waitcnt lgkmcnt(0)
	v_bfe_u32 v38, v52, 16, 1
	v_lshrrev_b32_e32 v37, 16, v37
	v_add3_u32 v38, v52, v38, s58
	v_and_or_b32 v37, v38, s59, v37
	buffer_store_dwordx4 v[34:37], v72, s[4:7], 0 offen sc1
	v_bfe_u32 v38, v53, 16, 1
	v_add3_u32 v38, v53, v38, s58
	v_bfe_u32 v34, v39, 16, 1
	v_add3_u32 v34, v39, v34, s58
	v_bfe_u32 v35, v41, 16, 1
	v_lshrrev_b32_e32 v34, 16, v34
	v_add3_u32 v35, v41, v35, s58
	v_and_or_b32 v34, v35, s59, v34
	v_bfe_u32 v35, v43, 16, 1
	v_add3_u32 v35, v43, v35, s58
	v_bfe_u32 v36, v45, 16, 1
	v_lshrrev_b32_e32 v35, 16, v35
	v_add3_u32 v36, v45, v36, s58
	v_and_or_b32 v35, v36, s59, v35
	v_bfe_u32 v36, v47, 16, 1
	v_add3_u32 v36, v47, v36, s58
	v_bfe_u32 v37, v49, 16, 1
	v_lshrrev_b32_e32 v36, 16, v36
	v_add3_u32 v37, v49, v37, s58
	v_and_or_b32 v36, v37, s59, v36
	v_bfe_u32 v37, v51, 16, 1
	v_add3_u32 v37, v51, v37, s58
	v_lshrrev_b32_e32 v37, 16, v37
	v_and_or_b32 v37, v38, s59, v37
	buffer_store_dwordx4 v[34:37], v73, s[4:7], 0 offen sc1
	s_waitcnt lgkmcnt(0)
	s_barrier
	s_and_saveexec_b64 s[4:5], s[2:3]
	s_cbranch_execz .LBB0_108
	s_mov_b64 s[40:41], exec
	v_mbcnt_lo_u32_b32 v34, s40, 0
	v_mbcnt_hi_u32_b32 v34, s41, v34
	v_cmp_eq_u32_e32 vcc, 0, v34
	s_and_b64 s[62:63], exec, vcc
	s_mov_b64 exec, s[62:63]
	s_cbranch_execz .LBB0_108
	s_bcnt1_i32_b64 s40, s[40:41]
	v_mov_b32_e32 v34, s40
	global_atomic_add v67, v34, s[30:31] offset:64
	s_branch .LBB0_108
